# GDN prep: zero-fill wait ladder removed; conv weights of the next unit requested in 5b behind the raw-window loads
# speedup vs baseline: 1.0077x; 1.0066x over previous
; __device__ __forceinline__ int fresh_lane() { int t; asm volatile("v_mbcnt_lo_u32_b32 %0, -1, 0\n\tv_mbcnt_hi_u32_b32 %0, -1, %0" : "=v"(t)); return t; }
;     ...
;         const int pair = t % 96, rg = t / 96, c0 = 2 * pair, part = c0 >> 6, d0 = c0 & 63, zcol = part * 256 + h * 64 + d0;
;         float cw[5][2];
; #pragma unroll
;         for (int j = 0; j < 5; ++j) { const float* wp = F.conv_w + (size_t)(l * 5 + j) * 768 + part * 256 + h * 64 + d0; cw[j][0] = wp[0]; cw[j][1] = wp[1]; }
; __global__ void __launch_bounds__(NWAVES * 64, 2) mk_fwd(Args args) {
;     ...
;                   if (!rep || PROBE_SUB != 2) { GdnPre GP; const int tpre = F.wave * 64 + fresh_lane(); gdn_preload(F, (int)blockIdx.x < 1152 ? (int)blockIdx.x : 1151, tpre, GP);
;                       for (int it = blockIdx.x; it < 1152; it += F.G) { const int nx = it + F.G < 1152 ? it + F.G : -1; gdn_prep_unit(F, l, it, GP, nx, 99, rep ? (bf16_t*)(F.ws + WS_H) : nullptr); } }
.LBB0_619:
	s_or_b64 exec, exec, s[10:11]
	v_readlane_b32 s0, v252, 0
	v_readlane_b32 s1, v252, 1
	s_andn2_b64 vcc, exec, s[0:1]
	s_cbranch_vccnz .LBB0_688
	v_readlane_b32 s1, v254, 37
	s_mul_i32 s0, s1, 5
	s_mul_i32 s62, s1, 0x3c00
	s_add_i32 s1, s0, 1
	s_mul_hi_i32 s21, s1, 0xc00
	s_add_i32 s1, s0, 2
	s_mul_hi_i32 s63, s0, 0xc00
	s_waitcnt lgkmcnt(0)
	s_mul_hi_i32 s23, s1, 0xc00
	s_add_i32 s1, s0, 3
	s_add_i32 s0, s0, 4
	s_add_i32 s20, s62, 0xc00
	s_add_i32 s22, s62, 0x1800
	s_add_i32 s24, s62, 0x2400
	s_mul_hi_i32 s25, s1, 0xc00
	s_add_i32 s26, s62, 0x3000
	s_mul_hi_i32 s27, s0, 0xc00
	s_mov_b32 s34, s72
	s_cmp_lt_u32 s64, 0x180
	s_cbranch_scc0 .Lcw_pro
	s_waitcnt lgkmcnt(0)
	v_mbcnt_lo_u32_b32 v4, -1, 0
	v_mbcnt_hi_u32_b32 v4, -1, v4
	v_add_u32_e32 v4, s64, v4
	s_mul_hi_i32 s0, s72, 0x38e38e39
	s_lshr_b32 s3, s0, 31
	s_ashr_i32 s0, s0, 3
	s_add_i32 s0, s0, s3
	s_and_b32 s0, s0, 3
	s_lshl_b32 s0, s0, 8
	s_mov_b32 s1, 0
	s_mov_b32 s3, 0x2aaaaaab
	v_mul_hi_i32 v5, v4, s3
	v_lshrrev_b32_e32 v6, 31, v5
	v_ashrrev_i32_e32 v5, 4, v5
	v_add_u32_e32 v5, v5, v6
	v_mul_u32_u24_e32 v5, 0x60, v5
	v_sub_u32_e32 v5, v4, v5
	v_lshlrev_b32_e32 v5, 3, v5
	v_and_b32_e32 v6, 0xffffff00, v5
	v_mov_b32_e32 v7, 0
	v_lshl_add_u64 v[6:7], v[6:7], 2, s[56:57]
	v_lshl_add_u64 v[6:7], v[6:7], 0, s[0:1]
	v_and_b32_e32 v10, 0xf8, v5
	v_mov_b32_e32 v11, 0
	v_lshl_add_u64 v[6:7], v[6:7], 0, v[10:11]
	v_lshl_add_u64 v[10:11], v[6:7], 0, s[62:63]
	global_load_dword v225, v[10:11], off
	global_load_dword v226, v[10:11], off offset:4
	v_lshl_add_u64 v[10:11], v[6:7], 0, s[20:21]
	global_load_dword v227, v[10:11], off
	global_load_dword v233, v[10:11], off offset:4
	v_lshl_add_u64 v[10:11], v[6:7], 0, s[22:23]
	global_load_dword v239, v[10:11], off
	global_load_dword v246, v[10:11], off offset:4
	v_lshl_add_u64 v[10:11], v[6:7], 0, s[24:25]
	global_load_dword v247, v[10:11], off
	global_load_dword v216, v[10:11], off offset:4
	v_lshl_add_u64 v[10:11], v[6:7], 0, s[26:27]
	global_load_dword v217, v[10:11], off
	global_load_dword v218, v[10:11], off offset:4
	global_load_dword v219, v[10:11], off
	global_load_dword v219, v[10:11], off
	global_load_dword v219, v[10:11], off
	global_load_dword v219, v[10:11], off
.Lcw_pro:
	s_branch .LBB0_622

; __device__ __forceinline__ float siluf_(float x) { return x * frcp(1.f + fexp(-x)); }
;     ...
;         const int pair = t % 96, rg = t / 96, c0 = 2 * pair, part = c0 >> 6, d0 = c0 & 63, zcol = part * 256 + h * 64 + d0;
;         float cw[5][2];
; #pragma unroll
;         for (int j = 0; j < 5; ++j) { const float* wp = F.conv_w + (size_t)(l * 5 + j) * 768 + part * 256 + h * 64 + d0; cw[j][0] = wp[0]; cw[j][1] = wp[1]; }
;         float win[20][2];
;         { const int rbase = row0 + rg * 16 - 2;
; #pragma unroll
;           for (int rr = 0; rr < 20; ++rr) { const int row = rbase + rr; const unsigned wv = (row >= seg_lo && row < seg_hi) ? P.raw[rr] : 0u; win[rr][0] = bflo(wv); win[rr][1] = bfhi(wv); } }
; #pragma unroll
;         for (int i = 0; i < 16; ++i) { float a0 = 0.f, a1 = 0.f;
; #pragma unroll
;             for (int j = 0; j < 5; ++j) { a0 += cw[j][0] * win[i + j][0]; a1 += cw[j][1] * win[i + j][1]; }
;             CV[(rg * 16 + i) * 196 + c0] = siluf_(a0); CV[(rg * 16 + i) * 196 + c0 + 1] = siluf_(a1); }
.LBB0_634:
	s_or_saveexec_b64 s[10:11], s[10:11]
	s_mov_b32 s5, 0x2aaaaaab
	v_mul_hi_i32 v0, v57, s5
	v_lshrrev_b32_e32 v65, 31, v0
	v_ashrrev_i32_e32 v69, 4, v0
	s_xor_b64 exec, exec, s[10:11]
	s_cbranch_execz .LBB0_636
	v_add_u32_e32 v60, v69, v65
	s_movk_i32 s5, 0x60
	v_mul_lo_u32 v0, v60, s5
	v_sub_u32_e32 v0, v57, v0
	v_lshlrev_b32_e32 v62, 3, v0
	v_lshlrev_b32_e32 v0, 4, v60
	s_add_i32 s3, s3, s0
	v_add3_u32 v10, s1, -2, v0
	v_cmp_le_i32_e32 vcc, s0, v10
	v_cmp_gt_i32_e64 s[40:41], s3, v10
	s_and_b64 vcc, vcc, s[40:41]
	s_waitcnt vmcnt(24)
	v_cndmask_b32_e32 v2, 0, v8, vcc
	v_lshlrev_b32_e32 v50, 16, v2
	v_and_b32_e32 v51, 0xffff0000, v2
	v_add_u32_e32 v2, 1, v10
	v_cmp_le_i32_e32 vcc, s0, v2
	v_cmp_gt_i32_e64 s[40:41], s3, v2
	s_and_b64 vcc, vcc, s[40:41]
	s_waitcnt vmcnt(23)
	v_cndmask_b32_e32 v2, 0, v9, vcc
	s_waitcnt vmcnt(22)
	v_lshlrev_b32_e32 v46, 16, v14
	v_and_b32_e32 v47, 0xffff0000, v14
	s_waitcnt vmcnt(21)
	v_lshlrev_b32_e32 v44, 16, v15
	v_and_b32_e32 v45, 0xffff0000, v15
	s_waitcnt vmcnt(20)
	v_lshlrev_b32_e32 v42, 16, v24
	v_and_b32_e32 v43, 0xffff0000, v24
	s_waitcnt vmcnt(19)
	v_lshlrev_b32_e32 v40, 16, v25
	v_and_b32_e32 v41, 0xffff0000, v25
	s_waitcnt vmcnt(18)
	v_lshlrev_b32_e32 v38, 16, v26
	v_and_b32_e32 v39, 0xffff0000, v26
	s_waitcnt vmcnt(17)
	v_lshlrev_b32_e32 v26, 16, v27
	v_and_b32_e32 v27, 0xffff0000, v27
	s_waitcnt vmcnt(16)
	v_lshlrev_b32_e32 v24, 16, v55
	v_and_b32_e32 v25, 0xffff0000, v55
	s_waitcnt vmcnt(15)
	v_lshlrev_b32_e32 v22, 16, v56
	v_and_b32_e32 v23, 0xffff0000, v56
	s_waitcnt vmcnt(14)
	v_lshlrev_b32_e32 v20, 16, v58
	v_and_b32_e32 v21, 0xffff0000, v58
	s_waitcnt vmcnt(13)
	v_lshlrev_b32_e32 v18, 16, v59
	v_and_b32_e32 v19, 0xffff0000, v59
	v_lshlrev_b32_e32 v48, 16, v2
	v_and_b32_e32 v49, 0xffff0000, v2
	s_waitcnt vmcnt(12)
	v_mov_b32_e32 v28, v225
	v_mov_b32_e32 v29, v226
	v_pk_fma_f32 v[50:51], v[28:29], v[50:51], 0 op_sel_hi:[1,1,0]
	s_waitcnt vmcnt(10)
	v_mov_b32_e32 v30, v227
	v_mov_b32_e32 v31, v233
	v_pk_fma_f32 v[50:51], v[30:31], v[48:49], v[50:51]
	s_waitcnt vmcnt(8)
	v_mov_b32_e32 v32, v239
	v_mov_b32_e32 v33, v246
	v_pk_fma_f32 v[50:51], v[32:33], v[46:47], v[50:51]
	v_lshlrev_b32_e32 v16, 16, v134
	v_and_b32_e32 v17, 0xffff0000, v134
	s_waitcnt vmcnt(6)
	v_mov_b32_e32 v34, v247
	v_mov_b32_e32 v35, v216
	v_pk_fma_f32 v[50:51], v[34:35], v[44:45], v[50:51]
	s_waitcnt vmcnt(4)
	v_mov_b32_e32 v36, v217
	v_mov_b32_e32 v37, v218
	v_pk_fma_f32 v[50:51], v[36:37], v[42:43], v[50:51]
	v_mul_f32_e32 v55, 0xbfb8aa3b, v50
	v_exp_f32_e32 v55, v55
	v_lshlrev_b32_e32 v14, 16, v135
	v_and_b32_e32 v15, 0xffff0000, v135
	v_add_f32_e32 v55, 1.0, v55
	v_lshlrev_b32_e32 v12, 16, v136
	v_and_b32_e32 v13, 0xffff0000, v136
	v_rcp_f32_e32 v58, v55
	v_mul_f32_e32 v55, 0xbfb8aa3b, v51
	v_exp_f32_e32 v55, v55
	v_pk_fma_f32 v[48:49], v[28:29], v[48:49], 0 op_sel_hi:[1,1,0]
	v_pk_fma_f32 v[48:49], v[30:31], v[46:47], v[48:49]
	v_pk_fma_f32 v[48:49], v[32:33], v[44:45], v[48:49]
	v_lshlrev_b32_e32 v2, 16, v137
	v_and_b32_e32 v3, 0xffff0000, v137
	v_pk_fma_f32 v[48:49], v[34:35], v[42:43], v[48:49]
	v_add_f32_e32 v55, 1.0, v55
	v_pk_fma_f32 v[48:49], v[36:37], v[40:41], v[48:49]
	v_rcp_f32_e32 v59, v55
	v_mul_f32_e32 v55, 0xbfb8aa3b, v48
	v_exp_f32_e32 v55, v55
	v_lshlrev_b32_e32 v4, 16, v138
	v_and_b32_e32 v5, 0xffff0000, v138
	v_add_f32_e32 v55, 1.0, v55
	v_lshlrev_b32_e32 v6, 16, v139
	v_and_b32_e32 v7, 0xffff0000, v139
	v_add_u32_e32 v0, 18, v10
	v_pk_mul_f32 v[50:51], v[50:51], v[58:59]
	v_rcp_f32_e32 v58, v55
	v_mul_f32_e32 v55, 0xbfb8aa3b, v49
	v_cmp_le_i32_e32 vcc, s0, v0
	v_cmp_gt_i32_e64 s[40:41], s3, v0
	v_exp_f32_e32 v55, v55
	s_and_b64 vcc, vcc, s[40:41]
	v_cndmask_b32_e32 v0, 0, v140, vcc
	v_lshlrev_b32_e32 v8, 16, v0
	v_and_b32_e32 v9, 0xffff0000, v0
	v_add_u32_e32 v0, 19, v10
	v_cmp_le_i32_e32 vcc, s0, v0
	v_cmp_gt_i32_e64 s[40:41], s3, v0
	v_add_f32_e32 v55, 1.0, v55
	s_and_b64 vcc, vcc, s[40:41]
	v_rcp_f32_e32 v59, v55
	v_pk_fma_f32 v[46:47], v[28:29], v[46:47], 0 op_sel_hi:[1,1,0]
	v_cndmask_b32_e32 v0, 0, v141, vcc
	s_movk_i32 s0, 0x3100
	v_pk_fma_f32 v[46:47], v[30:31], v[44:45], v[46:47]
	v_lshlrev_b32_e32 v10, 16, v0
	v_and_b32_e32 v11, 0xffff0000, v0
	v_mul_lo_u32 v0, v60, s0
	v_pk_fma_f32 v[46:47], v[32:33], v[42:43], v[46:47]
	v_add3_u32 v0, 0, v62, v0
	v_pk_fma_f32 v[46:47], v[34:35], v[40:41], v[46:47]
	v_pk_mul_f32 v[48:49], v[48:49], v[58:59]
	v_add_u32_e32 v55, 0x9800, v0
	v_pk_fma_f32 v[46:47], v[36:37], v[38:39], v[46:47]
	ds_write2_b64 v55, v[50:51], v[48:49] offset1:98
	v_mul_f32_e32 v48, 0xbfb8aa3b, v46
	v_mul_f32_e32 v49, 0xbfb8aa3b, v47
	v_exp_f32_e32 v48, v48
	v_exp_f32_e32 v49, v49
	v_pk_fma_f32 v[44:45], v[28:29], v[44:45], 0 op_sel_hi:[1,1,0]
	v_add_f32_e32 v48, 1.0, v48
	v_add_f32_e32 v49, 1.0, v49
	v_rcp_f32_e32 v48, v48
	v_rcp_f32_e32 v49, v49
	v_pk_fma_f32 v[44:45], v[30:31], v[42:43], v[44:45]
	v_pk_fma_f32 v[42:43], v[28:29], v[42:43], 0 op_sel_hi:[1,1,0]
	v_pk_fma_f32 v[44:45], v[32:33], v[40:41], v[44:45]
	v_pk_mul_f32 v[46:47], v[46:47], v[48:49]
	v_pk_fma_f32 v[44:45], v[34:35], v[38:39], v[44:45]
	v_pk_fma_f32 v[42:43], v[30:31], v[40:41], v[42:43]
	v_pk_fma_f32 v[44:45], v[36:37], v[26:27], v[44:45]
	v_pk_fma_f32 v[42:43], v[32:33], v[38:39], v[42:43]
	v_mul_f32_e32 v48, 0xbfb8aa3b, v44
	v_mul_f32_e32 v49, 0xbfb8aa3b, v45
	v_exp_f32_e32 v48, v48
	v_exp_f32_e32 v49, v49
	v_pk_fma_f32 v[42:43], v[34:35], v[26:27], v[42:43]
	v_pk_fma_f32 v[40:41], v[28:29], v[40:41], 0 op_sel_hi:[1,1,0]
	v_add_f32_e32 v48, 1.0, v48
	v_add_f32_e32 v49, 1.0, v49
	v_rcp_f32_e32 v48, v48
	v_rcp_f32_e32 v49, v49
	v_pk_fma_f32 v[42:43], v[36:37], v[24:25], v[42:43]
; __device__ __forceinline__ float siluf_(float x) { return x * frcp(1.f + fexp(-x)); }
;     ...
; #pragma unroll
;         for (int i = 0; i < 16; ++i) { float a0 = 0.f, a1 = 0.f;
; #pragma unroll
;             for (int j = 0; j < 5; ++j) { a0 += cw[j][0] * win[i + j][0]; a1 += cw[j][1] * win[i + j][1]; }
;             CV[(rg * 16 + i) * 196 + c0] = siluf_(a0); CV[(rg * 16 + i) * 196 + c0 + 1] = siluf_(a1); }
	v_pk_fma_f32 v[40:41], v[30:31], v[38:39], v[40:41]
	v_pk_fma_f32 v[38:39], v[28:29], v[38:39], 0 op_sel_hi:[1,1,0]
	v_pk_mul_f32 v[44:45], v[44:45], v[48:49]
	v_add_u32_e32 v48, 0x9c00, v0
	ds_write2_b64 v48, v[46:47], v[44:45] offset0:68 offset1:166
	v_mul_f32_e32 v44, 0xbfb8aa3b, v42
	v_mul_f32_e32 v45, 0xbfb8aa3b, v43
	v_exp_f32_e32 v44, v44
	v_exp_f32_e32 v45, v45
	v_pk_fma_f32 v[40:41], v[32:33], v[26:27], v[40:41]
	v_pk_fma_f32 v[38:39], v[30:31], v[26:27], v[38:39]
	v_add_f32_e32 v44, 1.0, v44
	v_add_f32_e32 v45, 1.0, v45
	v_rcp_f32_e32 v44, v44
	v_rcp_f32_e32 v45, v45
	v_pk_fma_f32 v[40:41], v[34:35], v[24:25], v[40:41]
	v_pk_fma_f32 v[38:39], v[32:33], v[24:25], v[38:39]
	v_pk_fma_f32 v[40:41], v[36:37], v[22:23], v[40:41]
	v_pk_mul_f32 v[42:43], v[42:43], v[44:45]
	v_mul_f32_e32 v44, 0xbfb8aa3b, v40
	v_mul_f32_e32 v45, 0xbfb8aa3b, v41
	v_exp_f32_e32 v44, v44
	v_exp_f32_e32 v45, v45
	v_pk_fma_f32 v[38:39], v[34:35], v[22:23], v[38:39]
	v_pk_fma_f32 v[26:27], v[28:29], v[26:27], 0 op_sel_hi:[1,1,0]
	v_add_f32_e32 v44, 1.0, v44
	v_add_f32_e32 v45, 1.0, v45
	v_rcp_f32_e32 v44, v44
	v_rcp_f32_e32 v45, v45
	v_pk_fma_f32 v[38:39], v[36:37], v[20:21], v[38:39]
	v_pk_fma_f32 v[26:27], v[30:31], v[24:25], v[26:27]
	v_pk_fma_f32 v[24:25], v[28:29], v[24:25], 0 op_sel_hi:[1,1,0]
	v_pk_mul_f32 v[40:41], v[40:41], v[44:45]
	v_add_u32_e32 v44, 0xa000, v0
	ds_write2_b64 v44, v[42:43], v[40:41] offset0:136 offset1:234
	v_mul_f32_e32 v40, 0xbfb8aa3b, v38
	v_mul_f32_e32 v41, 0xbfb8aa3b, v39
	v_exp_f32_e32 v40, v40
	v_exp_f32_e32 v41, v41
	v_pk_fma_f32 v[26:27], v[32:33], v[22:23], v[26:27]
	v_pk_fma_f32 v[24:25], v[30:31], v[22:23], v[24:25]
	v_add_f32_e32 v40, 1.0, v40
	v_add_f32_e32 v41, 1.0, v41
	v_rcp_f32_e32 v40, v40
	v_rcp_f32_e32 v41, v41
	v_pk_fma_f32 v[26:27], v[34:35], v[20:21], v[26:27]
	v_pk_fma_f32 v[24:25], v[32:33], v[20:21], v[24:25]
	v_pk_fma_f32 v[26:27], v[36:37], v[18:19], v[26:27]
	v_pk_mul_f32 v[38:39], v[38:39], v[40:41]
	v_mul_f32_e32 v40, 0xbfb8aa3b, v26
	v_mul_f32_e32 v41, 0xbfb8aa3b, v27
	v_exp_f32_e32 v40, v40
	v_exp_f32_e32 v41, v41
	v_pk_fma_f32 v[24:25], v[34:35], v[18:19], v[24:25]
	v_pk_fma_f32 v[22:23], v[28:29], v[22:23], 0 op_sel_hi:[1,1,0]
	v_add_f32_e32 v40, 1.0, v40
	v_add_f32_e32 v41, 1.0, v41
	v_rcp_f32_e32 v40, v40
	v_rcp_f32_e32 v41, v41
	v_pk_fma_f32 v[24:25], v[36:37], v[16:17], v[24:25]
	v_pk_fma_f32 v[22:23], v[30:31], v[20:21], v[22:23]
	v_pk_fma_f32 v[20:21], v[28:29], v[20:21], 0 op_sel_hi:[1,1,0]
	v_pk_mul_f32 v[26:27], v[26:27], v[40:41]
	v_add_u32_e32 v40, 0xa800, v0
	ds_write2_b64 v40, v[38:39], v[26:27] offset0:76 offset1:174
	v_mul_f32_e32 v26, 0xbfb8aa3b, v24
	v_mul_f32_e32 v27, 0xbfb8aa3b, v25
	v_exp_f32_e32 v26, v26
	v_exp_f32_e32 v27, v27
	v_pk_fma_f32 v[22:23], v[32:33], v[18:19], v[22:23]
	v_pk_fma_f32 v[20:21], v[30:31], v[18:19], v[20:21]
	v_add_f32_e32 v26, 1.0, v26
	v_add_f32_e32 v27, 1.0, v27
	v_rcp_f32_e32 v26, v26
	v_rcp_f32_e32 v27, v27
	v_pk_fma_f32 v[22:23], v[34:35], v[16:17], v[22:23]
	v_pk_fma_f32 v[20:21], v[32:33], v[16:17], v[20:21]
	v_pk_fma_f32 v[22:23], v[36:37], v[14:15], v[22:23]
	v_pk_mul_f32 v[24:25], v[24:25], v[26:27]
	v_mul_f32_e32 v26, 0xbfb8aa3b, v22
	v_mul_f32_e32 v27, 0xbfb8aa3b, v23
	v_exp_f32_e32 v26, v26
	v_exp_f32_e32 v27, v27
	v_pk_fma_f32 v[20:21], v[34:35], v[14:15], v[20:21]
	v_pk_fma_f32 v[18:19], v[28:29], v[18:19], 0 op_sel_hi:[1,1,0]
	v_add_f32_e32 v26, 1.0, v26
	v_add_f32_e32 v27, 1.0, v27
	v_rcp_f32_e32 v26, v26
	v_rcp_f32_e32 v27, v27
	v_pk_fma_f32 v[20:21], v[36:37], v[12:13], v[20:21]
	v_pk_fma_f32 v[18:19], v[30:31], v[16:17], v[18:19]
	v_pk_fma_f32 v[16:17], v[28:29], v[16:17], 0 op_sel_hi:[1,1,0]
	v_pk_mul_f32 v[22:23], v[22:23], v[26:27]
	v_add_u32_e32 v26, 0xb000, v0
	ds_write2_b64 v26, v[24:25], v[22:23] offset0:16 offset1:114
	v_mul_f32_e32 v22, 0xbfb8aa3b, v20
	v_mul_f32_e32 v23, 0xbfb8aa3b, v21
	v_exp_f32_e32 v22, v22
	v_exp_f32_e32 v23, v23
	v_pk_fma_f32 v[18:19], v[32:33], v[14:15], v[18:19]
	v_pk_fma_f32 v[16:17], v[30:31], v[14:15], v[16:17]
	v_add_f32_e32 v22, 1.0, v22
	v_add_f32_e32 v23, 1.0, v23
	v_rcp_f32_e32 v22, v22
	v_rcp_f32_e32 v23, v23
	v_pk_fma_f32 v[18:19], v[34:35], v[12:13], v[18:19]
	v_pk_fma_f32 v[16:17], v[32:33], v[12:13], v[16:17]
	v_pk_fma_f32 v[18:19], v[36:37], v[2:3], v[18:19]
	v_pk_mul_f32 v[20:21], v[20:21], v[22:23]
	v_mul_f32_e32 v22, 0xbfb8aa3b, v18
	v_mul_f32_e32 v23, 0xbfb8aa3b, v19
	v_exp_f32_e32 v22, v22
	v_exp_f32_e32 v23, v23
	v_pk_fma_f32 v[16:17], v[34:35], v[2:3], v[16:17]
	v_pk_fma_f32 v[14:15], v[28:29], v[14:15], 0 op_sel_hi:[1,1,0]
	v_add_f32_e32 v22, 1.0, v22
	v_add_f32_e32 v23, 1.0, v23
	v_rcp_f32_e32 v22, v22
	v_rcp_f32_e32 v23, v23
	v_pk_fma_f32 v[16:17], v[36:37], v[4:5], v[16:17]
	v_pk_fma_f32 v[14:15], v[30:31], v[12:13], v[14:15]
	v_pk_fma_f32 v[12:13], v[28:29], v[12:13], 0 op_sel_hi:[1,1,0]
	v_pk_mul_f32 v[18:19], v[18:19], v[22:23]
	v_add_u32_e32 v22, 0xb400, v0
	ds_write2_b64 v22, v[20:21], v[18:19] offset0:84 offset1:182
	v_mul_f32_e32 v18, 0xbfb8aa3b, v16
	v_mul_f32_e32 v19, 0xbfb8aa3b, v17
	v_exp_f32_e32 v18, v18
	v_exp_f32_e32 v19, v19
	v_pk_fma_f32 v[14:15], v[32:33], v[2:3], v[14:15]
	v_pk_fma_f32 v[12:13], v[30:31], v[2:3], v[12:13]
	v_add_f32_e32 v18, 1.0, v18
	v_add_f32_e32 v19, 1.0, v19
	v_rcp_f32_e32 v18, v18
	v_rcp_f32_e32 v19, v19
	v_pk_fma_f32 v[14:15], v[34:35], v[4:5], v[14:15]
	v_pk_fma_f32 v[2:3], v[28:29], v[2:3], 0 op_sel_hi:[1,1,0]
	v_pk_fma_f32 v[14:15], v[36:37], v[6:7], v[14:15]
	v_pk_mul_f32 v[16:17], v[16:17], v[18:19]
	v_mul_f32_e32 v18, 0xbfb8aa3b, v14
	v_mul_f32_e32 v19, 0xbfb8aa3b, v15
	v_exp_f32_e32 v18, v18
	v_exp_f32_e32 v19, v19
	v_pk_fma_f32 v[2:3], v[30:31], v[4:5], v[2:3]
	v_pk_fma_f32 v[12:13], v[32:33], v[4:5], v[12:13]
	v_add_f32_e32 v18, 1.0, v18
	v_add_f32_e32 v19, 1.0, v19
	v_rcp_f32_e32 v18, v18
	v_rcp_f32_e32 v19, v19
	v_pk_fma_f32 v[2:3], v[32:33], v[6:7], v[2:3]
	v_pk_fma_f32 v[12:13], v[34:35], v[6:7], v[12:13]
	v_pk_fma_f32 v[2:3], v[34:35], v[8:9], v[2:3]
	v_pk_mul_f32 v[14:15], v[14:15], v[18:19]
	v_add_u32_e32 v18, 0xb800, v0
	v_pk_fma_f32 v[12:13], v[36:37], v[8:9], v[12:13]
	v_pk_fma_f32 v[2:3], v[36:37], v[10:11], v[2:3]
	ds_write2_b64 v18, v[16:17], v[14:15] offset0:152 offset1:250
	v_mul_f32_e32 v14, 0xbfb8aa3b, v12
	v_mul_f32_e32 v15, 0xbfb8aa3b, v13
	v_mul_f32_e32 v4, 0xbfb8aa3b, v2
	v_mul_f32_e32 v5, 0xbfb8aa3b, v3
	v_exp_f32_e32 v14, v14
	v_exp_f32_e32 v15, v15
	v_exp_f32_e32 v4, v4
	v_exp_f32_e32 v5, v5
	v_add_f32_e32 v14, 1.0, v14
	v_add_f32_e32 v15, 1.0, v15
	v_add_f32_e32 v4, 1.0, v4
	v_add_f32_e32 v5, 1.0, v5
	v_rcp_f32_e32 v14, v14
	v_rcp_f32_e32 v15, v15
	v_rcp_f32_e32 v4, v4
	v_rcp_f32_e32 v5, v5
	v_add_u32_e32 v0, 0xc000, v0
	v_pk_mul_f32 v[12:13], v[12:13], v[14:15]
	v_pk_mul_f32 v[2:3], v[2:3], v[4:5]
	ds_write2_b64 v0, v[12:13], v[2:3] offset0:92 offset1:190

; #define LAS __attribute__((address_space(3)))
; __device__ __forceinline__ float fexp(float x) { return __builtin_amdgcn_exp2f(x * 1.4426950408889634f); }
; __device__ __forceinline__ v2u pack4(const f32x4 v) { v2u r; r.x = pk2(v[0], v[1]); r.y = pk2(v[2], v[3]); return r; }
; __device__ __forceinline__ f32x4 unpack4(const v2u w) { f32x4 r; r[0] = bflo(w.x); r[1] = bfhi(w.x); r[2] = bflo(w.y); r[3] = bfhi(w.y); return r; }
;     ...
;     for (int d = 0; d < 2; ++d) {
;         const int ud = u * 2 + d; const float tot = totS[d];
;         const LAS bf16_t* T0 = Tb + d * 9216; const LAS bf16_t* T1 = T0 + 4608; const LAS bf16_t* Ad = At + d * 4608;
;         {
;             const bool isw = w >= 4; const LAS bf16_t* Aop = isw ? T1 : T0; const LAS bf16_t* Bop = isw ? Kt : Vt;
;             LAS bf16_t* o0 = isw ? WT : UT; LAS bf16_t* o1 = isw ? WTd : UTd;
; #pragma unroll
;             for (int k4 = 0; k4 < 4; ++k4) { const int tt = (w & 3) * 4 + k4, mt = tt >> 2, nt = tt & 3;
;                 f32x4 acc = {0.f, 0.f, 0.f, 0.f}; acc = mma_ll<2>(Aop + mt * 16 * 72, 72, Bop + nt * 16 * 72, 72, acc, lane);
;                 const int n = nt * 16 + lr, m0 = mt * 16 + 4 * lq; f32x4 dv;
; #pragma unroll
;                 for (int i = 0; i < 4; ++i) dv[i] = acc[i] * gS[d * 64 + m0 + i];
;                 *(LAS v2u*)(o0 + n * 72 + m0) = pack4(acc); *(LAS v2u*)(o1 + n * 72 + m0) = pack4(dv); }
;         }
;         __syncthreads();
;         if (stop == 6) { __syncthreads(); continue; }
;         {
;             const int prod = w >> 1; bf16_t* gout = PGo + (size_t)ud * 16384 + prod * 4096;
;             const LAS bf16_t* Aop = prod == 0 ? WTd : prod == 1 ? Kt : prod == 2 ? WT : Ad;
;             const LAS bf16_t* Bop = prod == 0 ? Kt : prod == 1 ? UTd : prod == 2 ? Ad : UT;
;             v2u res[8];
; #pragma unroll
;             for (int k8 = 0; k8 < 8; ++k8) { const int tt = (w & 1) * 8 + k8, mt = tt >> 2, nt = tt & 3;
;                 f32x4 acc = {0.f, 0.f, 0.f, 0.f}; acc = mma_ll<2>(Aop + mt * 16 * 72, 72, Bop + nt * 16 * 72, 72, acc, lane);
;                 const int n = nt * 16 + lr, m0 = mt * 16 + 4 * lq;
;                 if (prod == 2) { const f32x4 qv = unpack4(*(const LAS v2u*)(Qs + n * 72 + m0)); const float e = 0.125f * fexp(gcS[d * 64 + n]); acc = qv * e - acc; }
;                 if (prod == 0) acc = -acc;
.LBB0_646:
	s_mul_i32 s12, s9, 0x4800
	v_add_u32_e32 v0, s12, v63
	v_lshl_add_u32 v210, s9, 8, v110
	ds_read_b128 v[142:145], v0
	ds_read_b128 v[154:157], v108
	ds_read_b128 v[158:161], v108 offset:2304
	ds_read_b128 v[162:165], v108 offset:4608
	ds_read_b128 v[166:169], v108 offset:6912
	ds_read_b128 v[146:149], v0 offset:64
	ds_read_b128 v[170:173], v108 offset:64
	ds_read_b128 v[176:179], v108 offset:2368
	ds_read_b128 v[180:183], v108 offset:4672
	ds_read_b128 v[184:187], v108 offset:6976
	ds_read_b128 v[150:153], v210 offset:36864
	s_waitcnt vmcnt(18)
	s_lshl_b32 s12, s9, 2
	s_add_i32 s14, s12, 0
	s_waitcnt vmcnt(17)
	v_mov_b32_e32 v14, s14
	ds_read_b32 v133, v14 offset:38400
	v_lshl_add_u32 v18, s9, 8, v110
	s_mul_i32 s12, s9, 0x2400
	s_add_i32 s12, s12, 0
	s_waitcnt vmcnt(16)
	s_add_i32 s15, s12, 0x1b800
	s_and_b64 s[12:13], s[30:31], exec
	s_cselect_b32 s33, s1, s15
	s_and_b64 s[12:13], s[28:29], exec
	s_cselect_b32 s33, s3, s33
	s_and_b64 s[12:13], s[40:41], exec
	s_cselect_b32 s33, s76, s33
	s_and_b64 vcc, s[30:31], exec
	s_cselect_b32 s15, s15, s2
	s_and_b64 s[12:13], s[28:29], exec
	s_cselect_b32 s15, s77, s15
	s_and_b64 s[12:13], s[40:41], exec
	s_cselect_b32 s12, s3, s15
	v_add3_u32 v28, s12, v113, v117
	s_mul_i32 s12, s9, 0xfc
	s_add_i32 s14, s14, s12
	v_lshl_add_u32 v0, v109, 2, s14
	v_add3_u32 v10, s33, v113, v117
	v_add_u32_e32 v11, s0, v10
	s_waitcnt lgkmcnt(10)
	v_mfma_f32_16x16x32_bf16 v[188:191], v[142:145], v[154:157], 0
	s_waitcnt lgkmcnt(9)
	v_mfma_f32_16x16x32_bf16 v[192:195], v[142:145], v[158:161], 0
	s_waitcnt lgkmcnt(8)
	v_mfma_f32_16x16x32_bf16 v[196:199], v[142:145], v[162:165], 0
	s_waitcnt lgkmcnt(7)
	v_mfma_f32_16x16x32_bf16 v[200:203], v[142:145], v[166:169], 0
	s_waitcnt lgkmcnt(5)
	v_mfma_f32_16x16x32_bf16 v[188:191], v[146:149], v[170:173], v[188:191]
	s_waitcnt lgkmcnt(4)
	v_mfma_f32_16x16x32_bf16 v[192:195], v[146:149], v[176:179], v[192:195]
	s_waitcnt lgkmcnt(3)
	v_mfma_f32_16x16x32_bf16 v[196:199], v[146:149], v[180:183], v[196:199]
	s_waitcnt lgkmcnt(2)
	v_mfma_f32_16x16x32_bf16 v[200:203], v[146:149], v[184:187], v[200:203]
	s_waitcnt lgkmcnt(1)
	s_nop 3
	v_pk_mul_f32 v[204:205], v[188:189], v[150:151]
	v_pk_mul_f32 v[206:207], v[190:191], v[152:153]
	v_cvt_pk_bf16_f32 v208, v188, v189
	v_cvt_pk_bf16_f32 v209, v190, v191
	ds_write_b64 v61, v[208:209]
	v_cvt_pk_bf16_f32 v204, v204, v205
	v_cvt_pk_bf16_f32 v205, v206, v207
	ds_write_b64 v111, v[204:205]
	v_pk_mul_f32 v[204:205], v[192:193], v[150:151]
	v_pk_mul_f32 v[206:207], v[194:195], v[152:153]
	v_cvt_pk_bf16_f32 v208, v192, v193
	v_cvt_pk_bf16_f32 v209, v194, v195
	ds_write_b64 v112, v[208:209]
	v_cvt_pk_bf16_f32 v204, v204, v205
	v_cvt_pk_bf16_f32 v205, v206, v207
	ds_write_b64 v114, v[204:205]
	v_pk_mul_f32 v[204:205], v[196:197], v[150:151]
	v_pk_mul_f32 v[206:207], v[198:199], v[152:153]
	v_cvt_pk_bf16_f32 v208, v196, v197
	v_cvt_pk_bf16_f32 v209, v198, v199
	ds_write_b64 v115, v[208:209]
	v_cvt_pk_bf16_f32 v204, v204, v205
	v_cvt_pk_bf16_f32 v205, v206, v207
	ds_write_b64 v116, v[204:205]
	v_pk_mul_f32 v[204:205], v[200:201], v[150:151]
	v_pk_mul_f32 v[206:207], v[202:203], v[152:153]
	v_cvt_pk_bf16_f32 v208, v200, v201
	v_cvt_pk_bf16_f32 v209, v202, v203
	ds_write_b64 v118, v[208:209]
	v_cvt_pk_bf16_f32 v204, v204, v205
	v_cvt_pk_bf16_f32 v205, v206, v207
	ds_write_b64 v119, v[204:205]
	s_waitcnt lgkmcnt(0)
	s_barrier
	ds_read_b128 v[142:145], v11
	ds_read_b128 v[158:161], v28
	ds_read_b128 v[162:165], v28 offset:2304
	ds_read_b128 v[166:169], v28 offset:4608
	ds_read_b128 v[170:173], v28 offset:6912
	ds_read_b128 v[150:153], v11 offset:2304
	ds_read_b128 v[146:149], v11 offset:64
	ds_read_b128 v[176:179], v28 offset:64
	ds_read_b128 v[180:183], v28 offset:2368
	ds_read_b128 v[184:187], v28 offset:4672
	ds_read_b128 v[188:191], v28 offset:6976
	ds_read_b128 v[154:157], v11 offset:2368
	s_waitcnt lgkmcnt(10)
	v_mfma_f32_16x16x32_bf16 v[2:5], v[142:145], v[158:161], 0
	s_waitcnt lgkmcnt(9)
	v_mfma_f32_16x16x32_bf16 v[6:9], v[142:145], v[162:165], 0
	s_waitcnt lgkmcnt(8)
	v_mfma_f32_16x16x32_bf16 v[12:15], v[142:145], v[166:169], 0
	s_waitcnt lgkmcnt(7)
	v_mfma_f32_16x16x32_bf16 v[20:23], v[142:145], v[170:173], 0
	s_waitcnt lgkmcnt(6)
	v_mfma_f32_16x16x32_bf16 v[24:27], v[150:153], v[158:161], 0
	v_mfma_f32_16x16x32_bf16 v[16:19], v[150:153], v[162:165], 0
	v_mfma_f32_16x16x32_bf16 v[36:39], v[150:153], v[166:169], 0
	v_mfma_f32_16x16x32_bf16 v[28:31], v[150:153], v[170:173], 0
	s_waitcnt lgkmcnt(4)
	v_mfma_f32_16x16x32_bf16 v[2:5], v[146:149], v[176:179], v[2:5]
	s_waitcnt lgkmcnt(3)
	v_mfma_f32_16x16x32_bf16 v[6:9], v[146:149], v[180:183], v[6:9]
	s_waitcnt lgkmcnt(2)
	v_mfma_f32_16x16x32_bf16 v[12:15], v[146:149], v[184:187], v[12:15]
	s_waitcnt lgkmcnt(1)
	v_mfma_f32_16x16x32_bf16 v[20:23], v[146:149], v[188:191], v[20:23]
	s_waitcnt lgkmcnt(0)
	v_mfma_f32_16x16x32_bf16 v[24:27], v[154:157], v[176:179], v[24:27]
	v_mfma_f32_16x16x32_bf16 v[16:19], v[154:157], v[180:183], v[16:19]
	v_mfma_f32_16x16x32_bf16 v[36:39], v[154:157], v[184:187], v[36:39]
	v_mfma_f32_16x16x32_bf16 v[28:31], v[154:157], v[188:191], v[28:31]
	s_and_b64 vcc, exec, s[30:31]
	s_cbranch_vccz .L5b_plain
; #define LAS __attribute__((address_space(3)))
; __device__ __forceinline__ float fexp(float x) { return __builtin_amdgcn_exp2f(x * 1.4426950408889634f); }
; __device__ __forceinline__ v2u pack4(const f32x4 v) { v2u r; r.x = pk2(v[0], v[1]); r.y = pk2(v[2], v[3]); return r; }
; __device__ __forceinline__ f32x4 unpack4(const v2u w) { f32x4 r; r[0] = bflo(w.x); r[1] = bfhi(w.x); r[2] = bflo(w.y); r[3] = bfhi(w.y); return r; }
;     ...
;                 f32x4 acc = {0.f, 0.f, 0.f, 0.f}; acc = mma_ll<2>(Aop + mt * 16 * 72, 72, Bop + nt * 16 * 72, 72, acc, lane);
;                 const int n = nt * 16 + lr, m0 = mt * 16 + 4 * lq;
;                 if (prod == 2) { const f32x4 qv = unpack4(*(const LAS v2u*)(Qs + n * 72 + m0)); const float e = 0.125f * fexp(gcS[d * 64 + n]); acc = qv * e - acc; }
;                 if (prod == 0) acc = -acc;
;                 res[k8] = pack4(acc); }
	v_add_u32_e32 v32, v121, v120
	v_add_u32_e32 v33, v122, v120
	ds_read_b32 v208, v0 offset:37888
	ds_read_b32 v210, v0 offset:37952
	ds_read_b32 v212, v0 offset:38016
	ds_read_b32 v214, v0 offset:38080
	ds_read_b64 v[192:193], v32
	ds_read_b64 v[194:195], v33
	ds_read_b64 v[196:197], v131
	ds_read_b64 v[198:199], v132
	ds_read_b64 v[200:201], v32 offset:32
	ds_read_b64 v[202:203], v33 offset:32
	ds_read_b64 v[204:205], v131 offset:32
	ds_read_b64 v[206:207], v132 offset:32
	s_waitcnt lgkmcnt(11)
	v_mul_f32_e32 v208, 0x3fb8aa3b, v208
	s_waitcnt lgkmcnt(10)
	v_mul_f32_e32 v210, 0x3fb8aa3b, v210
	s_waitcnt lgkmcnt(9)
	v_mul_f32_e32 v212, 0x3fb8aa3b, v212
	s_waitcnt lgkmcnt(8)
	v_mul_f32_e32 v214, 0x3fb8aa3b, v214
	v_exp_f32_e32 v208, v208
	v_exp_f32_e32 v210, v210
	v_exp_f32_e32 v212, v212
	v_exp_f32_e32 v214, v214
	v_mul_f32_e32 v208, 0x3e000000, v208
	v_mul_f32_e32 v210, 0x3e000000, v210
	v_mul_f32_e32 v212, 0x3e000000, v212
	v_mul_f32_e32 v214, 0x3e000000, v214
	s_waitcnt lgkmcnt(7)
	v_lshlrev_b32_e32 v40, 16, v192
	v_and_b32_e32 v41, 0xffff0000, v192
	v_lshlrev_b32_e32 v42, 16, v193
	v_and_b32_e32 v43, 0xffff0000, v193
	v_pk_fma_f32 v[2:3], v[208:209], v[40:41], v[2:3] op_sel_hi:[0,1,1] neg_lo:[0,0,1] neg_hi:[0,0,1]
	v_pk_fma_f32 v[4:5], v[208:209], v[42:43], v[4:5] op_sel_hi:[0,1,1] neg_lo:[0,0,1] neg_hi:[0,0,1]
	s_waitcnt lgkmcnt(6)
	v_lshlrev_b32_e32 v40, 16, v194
	v_and_b32_e32 v41, 0xffff0000, v194
	v_lshlrev_b32_e32 v42, 16, v195
	v_and_b32_e32 v43, 0xffff0000, v195
	v_pk_fma_f32 v[6:7], v[210:211], v[40:41], v[6:7] op_sel_hi:[0,1,1] neg_lo:[0,0,1] neg_hi:[0,0,1]
	v_pk_fma_f32 v[8:9], v[210:211], v[42:43], v[8:9] op_sel_hi:[0,1,1] neg_lo:[0,0,1] neg_hi:[0,0,1]
	s_waitcnt lgkmcnt(5)
	v_lshlrev_b32_e32 v40, 16, v196
	v_and_b32_e32 v41, 0xffff0000, v196
	v_lshlrev_b32_e32 v42, 16, v197
	v_and_b32_e32 v43, 0xffff0000, v197
	v_pk_fma_f32 v[12:13], v[212:213], v[40:41], v[12:13] op_sel_hi:[0,1,1] neg_lo:[0,0,1] neg_hi:[0,0,1]
	v_pk_fma_f32 v[14:15], v[212:213], v[42:43], v[14:15] op_sel_hi:[0,1,1] neg_lo:[0,0,1] neg_hi:[0,0,1]
	s_waitcnt lgkmcnt(4)
	v_lshlrev_b32_e32 v40, 16, v198
	v_and_b32_e32 v41, 0xffff0000, v198
	v_lshlrev_b32_e32 v42, 16, v199
	v_and_b32_e32 v43, 0xffff0000, v199
	v_pk_fma_f32 v[20:21], v[214:215], v[40:41], v[20:21] op_sel_hi:[0,1,1] neg_lo:[0,0,1] neg_hi:[0,0,1]
	v_pk_fma_f32 v[22:23], v[214:215], v[42:43], v[22:23] op_sel_hi:[0,1,1] neg_lo:[0,0,1] neg_hi:[0,0,1]
	s_waitcnt lgkmcnt(3)
	v_lshlrev_b32_e32 v40, 16, v200
	v_and_b32_e32 v41, 0xffff0000, v200
	v_lshlrev_b32_e32 v42, 16, v201
	v_and_b32_e32 v43, 0xffff0000, v201
	v_pk_fma_f32 v[24:25], v[208:209], v[40:41], v[24:25] op_sel_hi:[0,1,1] neg_lo:[0,0,1] neg_hi:[0,0,1]
	v_pk_fma_f32 v[26:27], v[208:209], v[42:43], v[26:27] op_sel_hi:[0,1,1] neg_lo:[0,0,1] neg_hi:[0,0,1]
	s_waitcnt lgkmcnt(2)
	v_lshlrev_b32_e32 v40, 16, v202
	v_and_b32_e32 v41, 0xffff0000, v202
	v_lshlrev_b32_e32 v42, 16, v203
	v_and_b32_e32 v43, 0xffff0000, v203
	v_pk_fma_f32 v[16:17], v[210:211], v[40:41], v[16:17] op_sel_hi:[0,1,1] neg_lo:[0,0,1] neg_hi:[0,0,1]
	v_pk_fma_f32 v[18:19], v[210:211], v[42:43], v[18:19] op_sel_hi:[0,1,1] neg_lo:[0,0,1] neg_hi:[0,0,1]
	s_waitcnt lgkmcnt(1)
	v_lshlrev_b32_e32 v40, 16, v204
	v_and_b32_e32 v41, 0xffff0000, v204
	v_lshlrev_b32_e32 v42, 16, v205
	v_and_b32_e32 v43, 0xffff0000, v205
	v_pk_fma_f32 v[36:37], v[212:213], v[40:41], v[36:37] op_sel_hi:[0,1,1] neg_lo:[0,0,1] neg_hi:[0,0,1]
	v_pk_fma_f32 v[38:39], v[212:213], v[42:43], v[38:39] op_sel_hi:[0,1,1] neg_lo:[0,0,1] neg_hi:[0,0,1]
	s_waitcnt lgkmcnt(0)
	v_lshlrev_b32_e32 v40, 16, v206
	v_and_b32_e32 v41, 0xffff0000, v206
	v_lshlrev_b32_e32 v42, 16, v207
	v_and_b32_e32 v43, 0xffff0000, v207
	v_pk_fma_f32 v[28:29], v[214:215], v[40:41], v[28:29] op_sel_hi:[0,1,1] neg_lo:[0,0,1] neg_hi:[0,0,1]
	v_pk_fma_f32 v[30:31], v[214:215], v[42:43], v[30:31] op_sel_hi:[0,1,1] neg_lo:[0,0,1] neg_hi:[0,0,1]
	s_branch .L5b_join

; __device__ __forceinline__ void gdn_preload(const Frame& F, int u, int t, GdnPre& P) {
;     ...
;         const int pair = t % 96, rg = t / 96, c0 = 2 * pair, part = c0 >> 6, d0 = c0 & 63, zcol = part * 256 + h * 64 + d0;
;         const int rbase = row0 + rg * 16 - 2; const bf16_t* zc = F.Z + zcol;
; #pragma unroll
;         for (int rr = 0; rr < 20; ++rr) { int row = rbase + rr; row = row < seg_lo ? seg_lo : (row >= seg_hi ? seg_hi - 1 : row); P.raw[rr] = *(const unsigned*)(zc + (size_t)row * ZW); }
;     ...
;         const int pair = t % 96, rg = t / 96, c0 = 2 * pair, part = c0 >> 6, d0 = c0 & 63, zcol = part * 256 + h * 64 + d0;
;         float cw[5][2];
; #pragma unroll
;         for (int j = 0; j < 5; ++j) { const float* wp = F.conv_w + (size_t)(l * 5 + j) * 768 + part * 256 + h * 64 + d0; cw[j][0] = wp[0]; cw[j][1] = wp[1]; }
.LBB0_664:
	s_or_saveexec_b64 s[44:45], s[12:13]
	s_xor_b64 exec, exec, s[44:45]
	s_cbranch_execz .LBB0_666
	s_cmp_eq_u32 s9, 0
	s_cbranch_scc1 .LBB0_666
	global_load_dword v8, v[68:69], off
	global_load_dword v9, v[70:71], off
	global_load_dword v14, v[72:73], off
	global_load_dword v15, v[74:75], off
	global_load_dword v24, v[76:77], off
	global_load_dword v25, v[78:79], off
	global_load_dword v26, v[80:81], off
	global_load_dword v27, v[82:83], off
	global_load_dword v55, v[84:85], off
	global_load_dword v56, v[86:87], off
	global_load_dword v58, v[88:89], off
	global_load_dword v59, v[90:91], off
	global_load_dword v134, v[92:93], off
	global_load_dword v135, v[94:95], off
	global_load_dword v136, v[96:97], off
	global_load_dword v137, v[98:99], off
	global_load_dword v138, v[100:101], off
	global_load_dword v139, v[102:103], off
	global_load_dword v140, v[104:105], off
	global_load_dword v141, v[106:107], off
	s_add_i32 s12, s4, 0xffffff00
	s_cmpk_lt_i32 s4, 0x480
	s_cselect_b32 s12, s4, s12
	s_mul_hi_i32 s14, s12, 0x38e38e39
	s_lshr_b32 s13, s14, 31
	s_ashr_i32 s14, s14, 3
	s_add_i32 s14, s14, s13
	s_and_b32 s14, s14, 3
	s_lshl_b32 s14, s14, 8
	s_mov_b32 s15, 0
	s_mov_b32 s48, 0x2aaaaaab
	v_mul_hi_i32 v0, v57, s48
	v_lshrrev_b32_e32 v32, 31, v0
	v_ashrrev_i32_e32 v0, 4, v0
	v_add_u32_e32 v0, v0, v32
	v_mul_u32_u24_e32 v0, 0x60, v0
	v_sub_u32_e32 v0, v57, v0
	v_lshlrev_b32_e32 v0, 3, v0
	v_and_b32_e32 v32, 0xffffff00, v0
	v_mov_b32_e32 v33, 0
	v_lshl_add_u64 v[32:33], v[32:33], 2, s[56:57]
	v_lshl_add_u64 v[32:33], v[32:33], 0, s[14:15]
	v_and_b32_e32 v34, 0xf8, v0
	v_mov_b32_e32 v35, 0
	v_lshl_add_u64 v[32:33], v[32:33], 0, v[34:35]
	v_lshl_add_u64 v[34:35], v[32:33], 0, s[62:63]
	global_load_dword v225, v[34:35], off
	global_load_dword v226, v[34:35], off offset:4
	v_lshl_add_u64 v[34:35], v[32:33], 0, s[20:21]
	global_load_dword v227, v[34:35], off
	global_load_dword v233, v[34:35], off offset:4
	v_lshl_add_u64 v[34:35], v[32:33], 0, s[22:23]
	global_load_dword v239, v[34:35], off
	global_load_dword v246, v[34:35], off offset:4
	v_lshl_add_u64 v[34:35], v[32:33], 0, s[24:25]
	global_load_dword v247, v[34:35], off
	global_load_dword v216, v[34:35], off offset:4
	v_lshl_add_u64 v[34:35], v[32:33], 0, s[26:27]
	global_load_dword v217, v[34:35], off
	global_load_dword v218, v[34:35], off offset:4
	v_mov_b32_e32 v2, 0
	v_mov_b32_e32 v3, 0
